# conv phase: the 30 halo rows + 8 tile rows are loaded in one batch (one wait) instead of five serial round trips, on top of the epilogue prefetch rings
# baseline (speedup 1.0000x reference)
; #define GLU2(uu) ((f32x2){bflo(uu), bfhi(uu)})
; __global__ void __launch_bounds__(NWAVES * 64, 2) mk_fwd(Args args) {
;     ...
;                 const int R0 = tile * 64, tl0 = R0 % SEQ;
;                 const bf16* zb = Z + (size_t)(R0 + 32 * th) * ZP + 2 * cp;
;                 f32x2 win[38]; unsigned ru[8];
; #pragma unroll
;                 for (int i = 0; i < 38; ++i) win[i] = (f32x2){0.f, 0.f};
;                 if (tl0 + 32 * th > 0) {
; #pragma unroll
;                     for (int i = 0; i < 30; ++i) { const bf16* zr = zb + (long)(i - 30) * ZP; const unsigned uu = *(const unsigned*)zr; win[8 + i] = GLU2(uu); } }
; #pragma unroll
;                 for (int i = 0; i < 8; ++i) { const bf16* zr = zb + (long)i * ZP; ru[i] = *(const unsigned*)zr; }
.LBB0_355:
	s_bfe_i32 s2, s6, 0x10019
	s_lshl_b32 s4, s6, 6
	s_lshr_b32 s2, s2, 21
	s_add_i32 s2, s4, s2
	s_and_b32 s2, s2, 0xfffff800
	v_add_u32_e32 v76, s4, v166
	s_sub_i32 s5, s4, s2
	v_mov_b32_e32 v81, v80
	v_mad_i64_i32 v[60:61], s[2:3], v76, s10, v[146:147]
	v_cmp_gt_i32_e32 vcc, s5, v167
	v_mov_b64_e32 v[64:65], v[80:81]
	v_mov_b64_e32 v[62:63], v[80:81]
	v_mov_b64_e32 v[56:57], v[80:81]
	v_mov_b64_e32 v[54:55], v[80:81]
	v_mov_b64_e32 v[52:53], v[80:81]
	v_mov_b64_e32 v[50:51], v[80:81]
	v_mov_b64_e32 v[38:39], v[80:81]
	v_mov_b64_e32 v[36:37], v[80:81]
	v_mov_b64_e32 v[34:35], v[80:81]
	v_mov_b64_e32 v[32:33], v[80:81]
	v_mov_b64_e32 v[30:31], v[80:81]
	v_mov_b64_e32 v[28:29], v[80:81]
	v_mov_b64_e32 v[26:27], v[80:81]
	v_mov_b64_e32 v[24:25], v[80:81]
	v_mov_b64_e32 v[22:23], v[80:81]
	v_mov_b64_e32 v[20:21], v[80:81]
	v_mov_b64_e32 v[18:19], v[80:81]
	v_mov_b64_e32 v[16:17], v[80:81]
	v_mov_b64_e32 v[46:47], v[80:81]
	v_mov_b64_e32 v[58:59], v[80:81]
	v_mov_b64_e32 v[70:71], v[80:81]
	v_mov_b64_e32 v[72:73], v[80:81]
	v_mov_b64_e32 v[74:75], v[80:81]
	v_mov_b64_e32 v[78:79], v[80:81]
	v_mov_b32_e32 v66, 0
	v_mov_b32_e32 v67, 0
	v_mov_b32_e32 v68, 0
	v_mov_b32_e32 v69, 0
	v_mov_b32_e32 v40, 0
	v_mov_b32_e32 v41, 0
	v_mov_b32_e32 v42, 0
	v_mov_b32_e32 v43, 0
	v_mov_b32_e32 v44, 0
	v_mov_b32_e32 v45, 0
	v_mov_b32_e32 v48, 0
	v_mov_b32_e32 v49, 0
	s_mov_b32 s92, 0x1400
	s_mov_b32 s93, 0
	s_mov_b32 s94, 0xfffda800
	s_mov_b32 s95, -1
	v_mov_b64_e32 v[242:243], v[60:61]
	global_load_dword v232, v[242:243], off
	v_lshl_add_u64 v[242:243], v[242:243], 0, s[92:93]
	global_load_dword v233, v[242:243], off
	v_lshl_add_u64 v[242:243], v[242:243], 0, s[92:93]
	global_load_dword v234, v[242:243], off
	v_lshl_add_u64 v[242:243], v[242:243], 0, s[92:93]
	global_load_dword v235, v[242:243], off
	v_lshl_add_u64 v[242:243], v[242:243], 0, s[92:93]
	global_load_dword v236, v[242:243], off
	v_lshl_add_u64 v[242:243], v[242:243], 0, s[92:93]
	global_load_dword v237, v[242:243], off
	v_lshl_add_u64 v[242:243], v[242:243], 0, s[92:93]
	global_load_dword v238, v[242:243], off
	v_lshl_add_u64 v[242:243], v[242:243], 0, s[92:93]
	global_load_dword v239, v[242:243], off
	s_and_saveexec_b64 s[2:3], vcc
	s_cbranch_execz .LBB0_357
	v_lshl_add_u64 v[240:241], v[60:61], 0, s[94:95]
	global_load_dword v201, v[240:241], off
	v_lshl_add_u64 v[240:241], v[240:241], 0, s[92:93]
	global_load_dword v202, v[240:241], off
	v_lshl_add_u64 v[240:241], v[240:241], 0, s[92:93]
	global_load_dword v203, v[240:241], off
	v_lshl_add_u64 v[240:241], v[240:241], 0, s[92:93]
	global_load_dword v204, v[240:241], off
	v_lshl_add_u64 v[240:241], v[240:241], 0, s[92:93]
	global_load_dword v205, v[240:241], off
	v_lshl_add_u64 v[240:241], v[240:241], 0, s[92:93]
	global_load_dword v206, v[240:241], off
	v_lshl_add_u64 v[240:241], v[240:241], 0, s[92:93]
	global_load_dword v207, v[240:241], off
	v_lshl_add_u64 v[240:241], v[240:241], 0, s[92:93]
	global_load_dword v208, v[240:241], off
	v_lshl_add_u64 v[240:241], v[240:241], 0, s[92:93]
	global_load_dword v209, v[240:241], off
	v_lshl_add_u64 v[240:241], v[240:241], 0, s[92:93]
	global_load_dword v210, v[240:241], off
	v_lshl_add_u64 v[240:241], v[240:241], 0, s[92:93]
	global_load_dword v211, v[240:241], off
	v_lshl_add_u64 v[240:241], v[240:241], 0, s[92:93]
	global_load_dword v212, v[240:241], off
	v_lshl_add_u64 v[240:241], v[240:241], 0, s[92:93]
	global_load_dword v213, v[240:241], off
	v_lshl_add_u64 v[240:241], v[240:241], 0, s[92:93]
	global_load_dword v214, v[240:241], off
	v_lshl_add_u64 v[240:241], v[240:241], 0, s[92:93]
	global_load_dword v215, v[240:241], off
	v_lshl_add_u64 v[240:241], v[240:241], 0, s[92:93]
	global_load_dword v216, v[240:241], off
	v_lshl_add_u64 v[240:241], v[240:241], 0, s[92:93]
	global_load_dword v217, v[240:241], off
	v_lshl_add_u64 v[240:241], v[240:241], 0, s[92:93]
	global_load_dword v218, v[240:241], off
	v_lshl_add_u64 v[240:241], v[240:241], 0, s[92:93]
	global_load_dword v219, v[240:241], off
	v_lshl_add_u64 v[240:241], v[240:241], 0, s[92:93]
	global_load_dword v221, v[240:241], off
	v_lshl_add_u64 v[240:241], v[240:241], 0, s[92:93]
	global_load_dword v222, v[240:241], off
	v_lshl_add_u64 v[240:241], v[240:241], 0, s[92:93]
	global_load_dword v223, v[240:241], off
	v_lshl_add_u64 v[240:241], v[240:241], 0, s[92:93]
	global_load_dword v224, v[240:241], off
	v_lshl_add_u64 v[240:241], v[240:241], 0, s[92:93]
	global_load_dword v225, v[240:241], off
	v_lshl_add_u64 v[240:241], v[240:241], 0, s[92:93]
	global_load_dword v226, v[240:241], off
	v_lshl_add_u64 v[240:241], v[240:241], 0, s[92:93]
	global_load_dword v227, v[240:241], off
	v_lshl_add_u64 v[240:241], v[240:241], 0, s[92:93]
	global_load_dword v228, v[240:241], off
	v_lshl_add_u64 v[240:241], v[240:241], 0, s[92:93]
	global_load_dword v229, v[240:241], off
	v_lshl_add_u64 v[240:241], v[240:241], 0, s[92:93]
	global_load_dword v230, v[240:241], off
	v_lshl_add_u64 v[240:241], v[240:241], 0, s[92:93]
	global_load_dword v231, v[240:241], off
	s_waitcnt vmcnt(0)
	v_add_co_u32_e32 v16, vcc, 0xfffda800, v60
	s_nop 1
	v_addc_co_u32_e32 v17, vcc, -1, v61, vcc
	v_add_co_u32_e32 v18, vcc, 0xfffdbc00, v60
	s_nop 1
	v_addc_co_u32_e32 v19, vcc, -1, v61, vcc
	v_add_co_u32_e32 v20, vcc, 0xfffdd000, v60
	s_nop 1
	v_addc_co_u32_e32 v21, vcc, -1, v61, vcc
	v_add_co_u32_e32 v22, vcc, 0xfffde400, v60
	s_nop 1
	v_addc_co_u32_e32 v23, vcc, -1, v61, vcc
	v_add_co_u32_e32 v24, vcc, 0xfffdf800, v60
	s_nop 1
	v_addc_co_u32_e32 v25, vcc, -1, v61, vcc
	v_add_co_u32_e32 v26, vcc, 0xfffe0c00, v60
	s_nop 1
	v_addc_co_u32_e32 v27, vcc, -1, v61, vcc
	v_add_co_u32_e32 v28, vcc, 0xfffe2000, v60
	s_nop 1
	v_addc_co_u32_e32 v29, vcc, -1, v61, vcc
	v_add_co_u32_e32 v30, vcc, 0xfffe3400, v60
	s_nop 1
	v_addc_co_u32_e32 v31, vcc, -1, v61, vcc
	v_mov_b32_e32 v32, v201
	v_mov_b32_e32 v33, v202
	v_mov_b32_e32 v34, v203
	v_mov_b32_e32 v35, v204
	v_mov_b32_e32 v36, v205
	v_mov_b32_e32 v37, v206
	v_mov_b32_e32 v38, v207
	v_mov_b32_e32 v39, v208
	v_add_co_u32_e32 v16, vcc, 0xfffe4800, v60
	s_waitcnt vmcnt(0) lgkmcnt(0)
; #define GLU2(uu) ((f32x2){bflo(uu), bfhi(uu)})
; __global__ void __launch_bounds__(NWAVES * 64, 2) mk_fwd(Args args) {
;     ...
;                 if (tl0 + 32 * th > 0) {
; #pragma unroll
;                     for (int i = 0; i < 30; ++i) { const bf16* zr = zb + (long)(i - 30) * ZP; const unsigned uu = *(const unsigned*)zr; win[8 + i] = GLU2(uu); } }
; #pragma unroll
;                 for (int i = 0; i < 8; ++i) { const bf16* zr = zb + (long)i * ZP; ru[i] = *(const unsigned*)zr; }
	v_lshlrev_b32_e32 v78, 16, v32
	v_addc_co_u32_e32 v17, vcc, -1, v61, vcc
	v_add_co_u32_e32 v18, vcc, 0xfffe5c00, v60
	v_and_b32_e32 v79, 0xffff0000, v32
	s_nop 0
	v_addc_co_u32_e32 v19, vcc, -1, v61, vcc
	v_add_co_u32_e32 v20, vcc, 0xfffe7000, v60
	v_lshlrev_b32_e32 v74, 16, v33
	s_nop 0
	v_addc_co_u32_e32 v21, vcc, -1, v61, vcc
	v_add_co_u32_e32 v22, vcc, 0xfffe8400, v60
	v_and_b32_e32 v75, 0xffff0000, v33
	s_nop 0
	v_addc_co_u32_e32 v23, vcc, -1, v61, vcc
	v_add_co_u32_e32 v24, vcc, 0xfffe9800, v60
	v_lshlrev_b32_e32 v72, 16, v34
	s_nop 0
	v_addc_co_u32_e32 v25, vcc, -1, v61, vcc
	v_add_co_u32_e32 v26, vcc, 0xfffeac00, v60
	v_and_b32_e32 v73, 0xffff0000, v34
	s_nop 0
	v_addc_co_u32_e32 v27, vcc, -1, v61, vcc
	v_add_co_u32_e32 v28, vcc, 0xfffec000, v60
	v_lshlrev_b32_e32 v70, 16, v35
	s_nop 0
	v_addc_co_u32_e32 v29, vcc, -1, v61, vcc
	v_add_co_u32_e32 v30, vcc, 0xfffed400, v60
	v_and_b32_e32 v71, 0xffff0000, v35
	s_nop 0
	v_addc_co_u32_e32 v31, vcc, -1, v61, vcc
	v_mov_b32_e32 v40, v209
	v_mov_b32_e32 v41, v210
	v_mov_b32_e32 v42, v211
	v_mov_b32_e32 v43, v212
	v_mov_b32_e32 v50, v213
	v_mov_b32_e32 v51, v214
	v_mov_b32_e32 v52, v215
	v_mov_b32_e32 v53, v216
	v_add_co_u32_e32 v16, vcc, 0xfffee800, v60
	v_lshlrev_b32_e32 v58, 16, v36
	s_nop 0
	v_addc_co_u32_e32 v17, vcc, -1, v61, vcc
	v_add_co_u32_e32 v18, vcc, 0xfffefc00, v60
	v_and_b32_e32 v59, 0xffff0000, v36
	s_nop 0
	v_addc_co_u32_e32 v19, vcc, -1, v61, vcc
	v_add_co_u32_e32 v20, vcc, 0xffff1000, v60
	v_lshlrev_b32_e32 v46, 16, v37
	s_nop 0
	v_addc_co_u32_e32 v21, vcc, -1, v61, vcc
	v_add_co_u32_e32 v22, vcc, 0xffff2400, v60
	v_and_b32_e32 v47, 0xffff0000, v37
	s_nop 0
	v_addc_co_u32_e32 v23, vcc, -1, v61, vcc
	v_add_co_u32_e32 v24, vcc, 0xffff3800, v60
	v_lshlrev_b32_e32 v48, 16, v38
	s_nop 0
	v_addc_co_u32_e32 v25, vcc, -1, v61, vcc
	v_add_co_u32_e32 v26, vcc, 0xffff4c00, v60
	v_and_b32_e32 v49, 0xffff0000, v38
	s_nop 0
	v_addc_co_u32_e32 v27, vcc, -1, v61, vcc
	v_add_co_u32_e32 v28, vcc, 0xffff6000, v60
	v_lshlrev_b32_e32 v44, 16, v39
	s_nop 0
	v_addc_co_u32_e32 v29, vcc, -1, v61, vcc
	v_add_co_u32_e32 v30, vcc, 0xffff7400, v60
	v_and_b32_e32 v45, 0xffff0000, v39
	s_nop 0
	v_addc_co_u32_e32 v31, vcc, -1, v61, vcc
	v_mov_b32_e32 v54, v217
	v_mov_b32_e32 v55, v218
	v_mov_b32_e32 v56, v219
	v_mov_b32_e32 v57, v221
	v_mov_b32_e32 v62, v222
	v_mov_b32_e32 v63, v223
	v_mov_b32_e32 v64, v224
	v_mov_b32_e32 v65, v225
	v_add_co_u32_e32 v16, vcc, 0xffff8800, v60
	s_waitcnt vmcnt(0) lgkmcnt(0)
	v_lshlrev_b32_e32 v26, 16, v51
	v_addc_co_u32_e32 v17, vcc, -1, v61, vcc
	v_add_co_u32_e32 v18, vcc, 0xffff9c00, v60
	v_and_b32_e32 v27, 0xffff0000, v51
	s_nop 0
	v_addc_co_u32_e32 v19, vcc, -1, v61, vcc
	v_add_co_u32_e32 v20, vcc, 0xffffb000, v60
	v_lshlrev_b32_e32 v28, 16, v54
	s_nop 0
	v_addc_co_u32_e32 v21, vcc, -1, v61, vcc
	v_add_co_u32_e32 v22, vcc, 0xffffc400, v60
	v_and_b32_e32 v29, 0xffff0000, v54
	s_nop 0
	v_addc_co_u32_e32 v23, vcc, -1, v61, vcc
	v_add_co_u32_e32 v24, vcc, 0xffffd800, v60
	v_lshlrev_b32_e32 v30, 16, v55
	s_nop 0
	v_addc_co_u32_e32 v25, vcc, -1, v61, vcc
	v_mov_b32_e32 v77, v226
	v_mov_b32_e32 v81, v227
	v_mov_b32_e32 v152, v228
	v_mov_b32_e32 v153, v229
	v_mov_b32_e32 v154, v230
	v_add_co_u32_e32 v16, vcc, 0xffffec00, v60
	v_lshlrev_b32_e32 v18, 16, v41
	s_nop 0
	v_addc_co_u32_e32 v17, vcc, -1, v61, vcc
	v_mov_b32_e32 v155, v231
	v_lshlrev_b32_e32 v16, 16, v40
	v_and_b32_e32 v17, 0xffff0000, v40
	v_and_b32_e32 v19, 0xffff0000, v41
	v_lshlrev_b32_e32 v20, 16, v42
	v_and_b32_e32 v21, 0xffff0000, v42
	v_lshlrev_b32_e32 v22, 16, v43
	v_and_b32_e32 v23, 0xffff0000, v43
	v_lshlrev_b32_e32 v24, 16, v50
	v_and_b32_e32 v25, 0xffff0000, v50
	v_lshlrev_b32_e32 v42, 16, v52
	v_and_b32_e32 v43, 0xffff0000, v52
	v_lshlrev_b32_e32 v40, 16, v53
	v_and_b32_e32 v41, 0xffff0000, v53
	v_and_b32_e32 v31, 0xffff0000, v55
	v_lshlrev_b32_e32 v32, 16, v56
	v_and_b32_e32 v33, 0xffff0000, v56
	v_lshlrev_b32_e32 v34, 16, v57
	v_and_b32_e32 v35, 0xffff0000, v57
	v_lshlrev_b32_e32 v36, 16, v62
	v_and_b32_e32 v37, 0xffff0000, v62
	v_lshlrev_b32_e32 v38, 16, v63
	v_and_b32_e32 v39, 0xffff0000, v63
	v_lshlrev_b32_e32 v68, 16, v64
	v_and_b32_e32 v69, 0xffff0000, v64
	v_lshlrev_b32_e32 v66, 16, v65
	v_and_b32_e32 v67, 0xffff0000, v65
	s_waitcnt vmcnt(0) lgkmcnt(0)
	v_lshlrev_b32_e32 v50, 16, v77
	v_and_b32_e32 v51, 0xffff0000, v77
	v_lshlrev_b32_e32 v52, 16, v81
	v_and_b32_e32 v53, 0xffff0000, v81
	v_lshlrev_b32_e32 v54, 16, v152
	v_and_b32_e32 v55, 0xffff0000, v152
	v_lshlrev_b32_e32 v56, 16, v153
	v_and_b32_e32 v57, 0xffff0000, v153
	v_lshlrev_b32_e32 v62, 16, v154
	v_and_b32_e32 v63, 0xffff0000, v154
	v_lshlrev_b32_e32 v64, 16, v155
	v_and_b32_e32 v65, 0xffff0000, v155
.LBB0_357:
	s_or_b64 exec, exec, s[2:3]
	s_waitcnt vmcnt(0)
	v_add_co_u32_e32 v152, vcc, s7, v60
	v_mov_b32_e32 v81, v175
	s_nop 0
	v_addc_co_u32_e32 v153, vcc, 0, v61, vcc
	v_add_co_u32_e32 v154, vcc, s8, v60
	s_nop 1
	v_addc_co_u32_e32 v155, vcc, 0, v61, vcc
	v_add_co_u32_e32 v156, vcc, s9, v60
	s_nop 1
	v_addc_co_u32_e32 v157, vcc, 0, v61, vcc
	v_add_co_u32_e32 v158, vcc, s12, v60
	s_nop 1
	v_addc_co_u32_e32 v159, vcc, 0, v61, vcc
	v_add_co_u32_e32 v160, vcc, 0x6000, v60
	s_nop 1
	v_addc_co_u32_e32 v161, vcc, 0, v61, vcc
	v_add_co_u32_e32 v162, vcc, 0x7000, v60
	s_nop 1
	v_addc_co_u32_e32 v163, vcc, 0, v61, vcc
	v_add_co_u32_e32 v164, vcc, 0x8000, v60
	s_nop 1
	v_addc_co_u32_e32 v165, vcc, 0, v61, vcc
	v_mov_b32_e32 v192, v233
	v_mov_b32_e32 v191, v234
	v_mov_b32_e32 v190, v235
	v_mov_b32_e32 v189, v236
	v_mov_b32_e32 v188, v237
	v_mov_b32_e32 v187, v238
	v_mov_b32_e32 v186, v239
	v_mov_b32_e32 v193, v232
	v_mad_i64_i32 v[60:61], s[2:3], v76, s10, 0
	s_mov_b64 s[2:3], 0
	v_lshl_add_u64 v[60:61], v[150:151], 0, v[60:61]
	s_waitcnt vmcnt(0) lgkmcnt(0)
	v_mov_b32_e32 v178, v192
	v_mov_b32_e32 v179, v191
	v_mov_b32_e32 v180, v190
	v_mov_b32_e32 v181, v189
	v_mov_b32_e32 v183, v188
	v_mov_b32_e32 v184, v187
	v_mov_b32_e32 v185, v186
	v_mov_b32_e32 v182, v193
	s_branch .LBB0_359
